# speedup vs baseline: 1.0947x; 1.0057x over previous
; __device__ __forceinline__ float sigmoidf_(float x) { return __builtin_amdgcn_rcpf(1.0f + __expf(-x)); }
; __device__ __forceinline__ void gemm_phase(const GemmArgs& a, char* smem) {
;     ...
;     } else if (emode == 1) {
; #pragma unroll
;       for (int ai = 0; ai < 2; ++ai)
; #pragma unroll
;         for (int m = 0; m < 4; ++m) {
;           const int row = brow + ai * 128 + wr * 64 + m * 16 + fr;
;           const float r = rr[ai][m];
; #pragma unroll
;           for (int n = 0; n < 2; ++n) {
;             const int col = (bcol >> 1) + wc * 32 + n * 16 + fq * 4;
;             float h[4];
; #pragma unroll
;             for (int j = 0; j < 4; ++j) {
;               const float g = acc[ai][0][m][n][j] * r, uu = acc[ai][1][m][n][j] * r;
;               h[j] = g * sigmoidf_(g) * uu;
;             }
;             uint2 pk;
;             pk.x = pack2(h[0], h[1]);
;             pk.y = pack2(h[2], h[3]);
;             *(uint2*)(a.outb + (long)row * a.ldo + col) = pk;
;           }
;         }
.LBB0_258:
	s_and_b64 vcc, exec, s[6:7]
	s_cbranch_vccz .LBB0_260
	s_ashr_i32 s2, s56, 1
	s_mov_b32 s10, 0xbfb8aa3b
	s_mov_b32 s11, 0xbfb8aa3b
	v_lshlrev_b32_e32 v128, 5, v190
	v_and_b32_e32 v129, 1, v189
	v_lshrrev_b32_e32 v130, 1, v189
	v_lshlrev_b32_e32 v129, 4, v129
	v_lshl_add_u32 v129, v130, 3, v129
	v_add3_u32 v128, v128, s2, v129
	v_ashrrev_i32_e32 v129, 31, v128
	v_mad_i64_i32 v[132:133], s[2:3], s82, v158, 0
	v_lshl_add_u64 v[132:133], v[132:133], 1, s[60:61]
	v_lshl_add_u64 v[132:133], v[128:129], 1, v[132:133]
	s_lshl_b32 s8, s82, 5
	s_mov_b32 s9, 0
	v_pk_mul_f32 v[130:131], v[116:117], v[156:157] op_sel:[0,1]
	v_pk_mul_f32 v[138:139], v[118:119], v[156:157] op_sel:[0,1]
	v_pk_mul_f32 v[134:135], v[124:125], v[156:157] op_sel:[0,1]
	v_pk_mul_f32 v[140:141], v[126:127], v[156:157] op_sel:[0,1]
	v_pk_mul_f32 v[136:137], v[130:131], s[10:11]
	v_pk_mul_f32 v[142:143], v[138:139], s[10:11]
	v_exp_f32_e32 v136, v136
	v_exp_f32_e32 v137, v137
	v_exp_f32_e32 v142, v142
	v_exp_f32_e32 v143, v143
	v_pk_add_f32 v[136:137], v[136:137], 1.0 op_sel_hi:[1,0]
	v_pk_add_f32 v[142:143], v[142:143], 1.0 op_sel_hi:[1,0]
	v_rcp_f32_e32 v136, v136
	v_rcp_f32_e32 v137, v137
	v_rcp_f32_e32 v142, v142
	v_rcp_f32_e32 v143, v143
	s_nop 0
	v_pk_mul_f32 v[130:131], v[130:131], v[136:137]
	v_pk_mul_f32 v[138:139], v[138:139], v[142:143]
	v_pk_mul_f32 v[130:131], v[134:135], v[130:131]
	v_pk_mul_f32 v[138:139], v[140:141], v[138:139]
	v_cvt_pk_bf16_f32 v144, v130, v131
	v_cvt_pk_bf16_f32 v145, v138, v139
	v_pk_mul_f32 v[130:131], v[112:113], v[156:157] op_sel:[0,1]
	v_pk_mul_f32 v[138:139], v[114:115], v[156:157] op_sel:[0,1]
	v_pk_mul_f32 v[134:135], v[120:121], v[156:157] op_sel:[0,1]
	v_pk_mul_f32 v[140:141], v[122:123], v[156:157] op_sel:[0,1]
	v_pk_mul_f32 v[136:137], v[130:131], s[10:11]
	v_pk_mul_f32 v[142:143], v[138:139], s[10:11]
	v_exp_f32_e32 v136, v136
	v_exp_f32_e32 v137, v137
	v_exp_f32_e32 v142, v142
	v_exp_f32_e32 v143, v143
	v_pk_add_f32 v[136:137], v[136:137], 1.0 op_sel_hi:[1,0]
	v_pk_add_f32 v[142:143], v[142:143], 1.0 op_sel_hi:[1,0]
	v_rcp_f32_e32 v136, v136
	v_rcp_f32_e32 v137, v137
	v_rcp_f32_e32 v142, v142
	v_rcp_f32_e32 v143, v143
	s_nop 0
	v_pk_mul_f32 v[130:131], v[130:131], v[136:137]
	v_pk_mul_f32 v[138:139], v[138:139], v[142:143]
	v_pk_mul_f32 v[130:131], v[134:135], v[130:131]
	v_pk_mul_f32 v[138:139], v[140:141], v[138:139]
	v_cvt_pk_bf16_f32 v146, v130, v131
	v_cvt_pk_bf16_f32 v147, v138, v139
	s_nop 1
	v_permlane16_swap_b32_e32 v144, v146
	v_permlane16_swap_b32_e32 v145, v147
	global_store_dwordx4 v[132:133], v[144:147], off
	v_lshl_add_u64 v[132:133], v[132:133], 0, s[8:9]
	v_pk_mul_f32 v[130:131], v[96:97], v[156:157] op_sel_hi:[1,0]
	v_pk_mul_f32 v[138:139], v[98:99], v[156:157] op_sel_hi:[1,0]
	v_pk_mul_f32 v[134:135], v[104:105], v[156:157] op_sel_hi:[1,0]
	v_pk_mul_f32 v[140:141], v[106:107], v[156:157] op_sel_hi:[1,0]
	v_pk_mul_f32 v[136:137], v[130:131], s[10:11]
	v_pk_mul_f32 v[142:143], v[138:139], s[10:11]
	v_exp_f32_e32 v136, v136
	v_exp_f32_e32 v137, v137
	v_exp_f32_e32 v142, v142
	v_exp_f32_e32 v143, v143
	v_pk_add_f32 v[136:137], v[136:137], 1.0 op_sel_hi:[1,0]
	v_pk_add_f32 v[142:143], v[142:143], 1.0 op_sel_hi:[1,0]
	v_rcp_f32_e32 v136, v136
	v_rcp_f32_e32 v137, v137
	v_rcp_f32_e32 v142, v142
	v_rcp_f32_e32 v143, v143
	s_nop 0
	v_pk_mul_f32 v[130:131], v[130:131], v[136:137]
	v_pk_mul_f32 v[138:139], v[138:139], v[142:143]
	v_pk_mul_f32 v[130:131], v[134:135], v[130:131]
	v_pk_mul_f32 v[138:139], v[140:141], v[138:139]
	v_cvt_pk_bf16_f32 v148, v130, v131
	v_cvt_pk_bf16_f32 v149, v138, v139
	v_pk_mul_f32 v[130:131], v[100:101], v[156:157] op_sel_hi:[1,0]
	v_pk_mul_f32 v[138:139], v[102:103], v[156:157] op_sel_hi:[1,0]
	v_pk_mul_f32 v[134:135], v[108:109], v[156:157] op_sel_hi:[1,0]
	v_pk_mul_f32 v[140:141], v[110:111], v[156:157] op_sel_hi:[1,0]
	v_pk_mul_f32 v[136:137], v[130:131], s[10:11]
	v_pk_mul_f32 v[142:143], v[138:139], s[10:11]
	v_exp_f32_e32 v136, v136
	v_exp_f32_e32 v137, v137
	v_exp_f32_e32 v142, v142
	v_exp_f32_e32 v143, v143
	v_pk_add_f32 v[136:137], v[136:137], 1.0 op_sel_hi:[1,0]
	v_pk_add_f32 v[142:143], v[142:143], 1.0 op_sel_hi:[1,0]
	v_rcp_f32_e32 v136, v136
	v_rcp_f32_e32 v137, v137
	v_rcp_f32_e32 v142, v142
	v_rcp_f32_e32 v143, v143
	s_nop 0
	v_pk_mul_f32 v[130:131], v[130:131], v[136:137]
	v_pk_mul_f32 v[138:139], v[138:139], v[142:143]
	v_pk_mul_f32 v[130:131], v[134:135], v[130:131]
	v_pk_mul_f32 v[138:139], v[140:141], v[138:139]
	v_cvt_pk_bf16_f32 v150, v130, v131
	v_cvt_pk_bf16_f32 v151, v138, v139
	s_nop 1
	v_permlane16_swap_b32_e32 v148, v150
	v_permlane16_swap_b32_e32 v149, v151
	global_store_dwordx4 v[132:133], v[148:151], off
	v_lshl_add_u64 v[132:133], v[132:133], 0, s[8:9]
	v_pk_mul_f32 v[130:131], v[80:81], v[160:161] op_sel:[0,1]
	v_pk_mul_f32 v[138:139], v[82:83], v[160:161] op_sel:[0,1]
	v_pk_mul_f32 v[134:135], v[88:89], v[160:161] op_sel:[0,1]
	v_pk_mul_f32 v[140:141], v[90:91], v[160:161] op_sel:[0,1]
	v_pk_mul_f32 v[136:137], v[130:131], s[10:11]
	v_pk_mul_f32 v[142:143], v[138:139], s[10:11]
	v_exp_f32_e32 v136, v136
	v_exp_f32_e32 v137, v137
	v_exp_f32_e32 v142, v142
	v_exp_f32_e32 v143, v143
	v_pk_add_f32 v[136:137], v[136:137], 1.0 op_sel_hi:[1,0]
	v_pk_add_f32 v[142:143], v[142:143], 1.0 op_sel_hi:[1,0]
	v_rcp_f32_e32 v136, v136
	v_rcp_f32_e32 v137, v137
	v_rcp_f32_e32 v142, v142
	v_rcp_f32_e32 v143, v143
	s_nop 0
	v_pk_mul_f32 v[130:131], v[130:131], v[136:137]
	v_pk_mul_f32 v[138:139], v[138:139], v[142:143]
	v_pk_mul_f32 v[130:131], v[134:135], v[130:131]
	v_pk_mul_f32 v[138:139], v[140:141], v[138:139]
	v_cvt_pk_bf16_f32 v144, v130, v131
; __device__ __forceinline__ float sigmoidf_(float x) { return __builtin_amdgcn_rcpf(1.0f + __expf(-x)); }
; __device__ __forceinline__ void gemm_phase(const GemmArgs& a, char* smem) {
;     ...
;     } else if (emode == 1) {
; #pragma unroll
;       for (int ai = 0; ai < 2; ++ai)
; #pragma unroll
;         for (int m = 0; m < 4; ++m) {
;           const int row = brow + ai * 128 + wr * 64 + m * 16 + fr;
;           const float r = rr[ai][m];
; #pragma unroll
;           for (int n = 0; n < 2; ++n) {
;             const int col = (bcol >> 1) + wc * 32 + n * 16 + fq * 4;
;             float h[4];
; #pragma unroll
;             for (int j = 0; j < 4; ++j) {
;               const float g = acc[ai][0][m][n][j] * r, uu = acc[ai][1][m][n][j] * r;
;               h[j] = g * sigmoidf_(g) * uu;
;             }
;             uint2 pk;
;             pk.x = pack2(h[0], h[1]);
;             pk.y = pack2(h[2], h[3]);
;             *(uint2*)(a.outb + (long)row * a.ldo + col) = pk;
;           }
;         }
	v_cvt_pk_bf16_f32 v145, v138, v139
	v_pk_mul_f32 v[130:131], v[84:85], v[160:161] op_sel:[0,1]
	v_pk_mul_f32 v[138:139], v[86:87], v[160:161] op_sel:[0,1]
	v_pk_mul_f32 v[134:135], v[92:93], v[160:161] op_sel:[0,1]
	v_pk_mul_f32 v[140:141], v[94:95], v[160:161] op_sel:[0,1]
	v_pk_mul_f32 v[136:137], v[130:131], s[10:11]
	v_pk_mul_f32 v[142:143], v[138:139], s[10:11]
	v_exp_f32_e32 v136, v136
	v_exp_f32_e32 v137, v137
	v_exp_f32_e32 v142, v142
	v_exp_f32_e32 v143, v143
	v_pk_add_f32 v[136:137], v[136:137], 1.0 op_sel_hi:[1,0]
	v_pk_add_f32 v[142:143], v[142:143], 1.0 op_sel_hi:[1,0]
	v_rcp_f32_e32 v136, v136
	v_rcp_f32_e32 v137, v137
	v_rcp_f32_e32 v142, v142
	v_rcp_f32_e32 v143, v143
	s_nop 0
	v_pk_mul_f32 v[130:131], v[130:131], v[136:137]
	v_pk_mul_f32 v[138:139], v[138:139], v[142:143]
	v_pk_mul_f32 v[130:131], v[134:135], v[130:131]
	v_pk_mul_f32 v[138:139], v[140:141], v[138:139]
	v_cvt_pk_bf16_f32 v146, v130, v131
	v_cvt_pk_bf16_f32 v147, v138, v139
	s_nop 1
	v_permlane16_swap_b32_e32 v144, v146
	v_permlane16_swap_b32_e32 v145, v147
	global_store_dwordx4 v[132:133], v[144:147], off
	v_lshl_add_u64 v[132:133], v[132:133], 0, s[8:9]
	v_pk_mul_f32 v[130:131], v[64:65], v[160:161] op_sel_hi:[1,0]
	v_pk_mul_f32 v[138:139], v[66:67], v[160:161] op_sel_hi:[1,0]
	v_pk_mul_f32 v[134:135], v[72:73], v[160:161] op_sel_hi:[1,0]
	v_pk_mul_f32 v[140:141], v[74:75], v[160:161] op_sel_hi:[1,0]
	v_pk_mul_f32 v[136:137], v[130:131], s[10:11]
	v_pk_mul_f32 v[142:143], v[138:139], s[10:11]
	v_exp_f32_e32 v136, v136
	v_exp_f32_e32 v137, v137
	v_exp_f32_e32 v142, v142
	v_exp_f32_e32 v143, v143
	v_pk_add_f32 v[136:137], v[136:137], 1.0 op_sel_hi:[1,0]
	v_pk_add_f32 v[142:143], v[142:143], 1.0 op_sel_hi:[1,0]
	v_rcp_f32_e32 v136, v136
	v_rcp_f32_e32 v137, v137
	v_rcp_f32_e32 v142, v142
	v_rcp_f32_e32 v143, v143
	s_nop 0
	v_pk_mul_f32 v[130:131], v[130:131], v[136:137]
	v_pk_mul_f32 v[138:139], v[138:139], v[142:143]
	v_pk_mul_f32 v[130:131], v[134:135], v[130:131]
	v_pk_mul_f32 v[138:139], v[140:141], v[138:139]
	v_cvt_pk_bf16_f32 v148, v130, v131
	v_cvt_pk_bf16_f32 v149, v138, v139
	v_pk_mul_f32 v[130:131], v[68:69], v[160:161] op_sel_hi:[1,0]
	v_pk_mul_f32 v[138:139], v[70:71], v[160:161] op_sel_hi:[1,0]
	v_pk_mul_f32 v[134:135], v[76:77], v[160:161] op_sel_hi:[1,0]
	v_pk_mul_f32 v[140:141], v[78:79], v[160:161] op_sel_hi:[1,0]
	v_pk_mul_f32 v[136:137], v[130:131], s[10:11]
	v_pk_mul_f32 v[142:143], v[138:139], s[10:11]
	v_exp_f32_e32 v136, v136
	v_exp_f32_e32 v137, v137
	v_exp_f32_e32 v142, v142
	v_exp_f32_e32 v143, v143
	v_pk_add_f32 v[136:137], v[136:137], 1.0 op_sel_hi:[1,0]
	v_pk_add_f32 v[142:143], v[142:143], 1.0 op_sel_hi:[1,0]
	v_rcp_f32_e32 v136, v136
	v_rcp_f32_e32 v137, v137
	v_rcp_f32_e32 v142, v142
	v_rcp_f32_e32 v143, v143
	s_nop 0
	v_pk_mul_f32 v[130:131], v[130:131], v[136:137]
	v_pk_mul_f32 v[138:139], v[138:139], v[142:143]
	v_pk_mul_f32 v[130:131], v[134:135], v[130:131]
	v_pk_mul_f32 v[138:139], v[140:141], v[138:139]
	v_cvt_pk_bf16_f32 v150, v130, v131
	v_cvt_pk_bf16_f32 v151, v138, v139
	s_nop 1
	v_permlane16_swap_b32_e32 v148, v150
	v_permlane16_swap_b32_e32 v149, v151
	global_store_dwordx4 v[132:133], v[148:151], off
	v_lshl_add_u64 v[132:133], v[132:133], 0, s[8:9]
	v_lshl_add_u64 v[132:133], v[132:133], 0, s[8:9]
	v_lshl_add_u64 v[132:133], v[132:133], 0, s[8:9]
	v_lshl_add_u64 v[132:133], v[132:133], 0, s[8:9]
	v_lshl_add_u64 v[132:133], v[132:133], 0, s[8:9]
	v_pk_mul_f32 v[130:131], v[48:49], v[162:163] op_sel:[0,1]
	v_pk_mul_f32 v[138:139], v[50:51], v[162:163] op_sel:[0,1]
	v_pk_mul_f32 v[134:135], v[56:57], v[162:163] op_sel:[0,1]
	v_pk_mul_f32 v[140:141], v[58:59], v[162:163] op_sel:[0,1]
	v_pk_mul_f32 v[136:137], v[130:131], s[10:11]
	v_pk_mul_f32 v[142:143], v[138:139], s[10:11]
	v_exp_f32_e32 v136, v136
	v_exp_f32_e32 v137, v137
	v_exp_f32_e32 v142, v142
	v_exp_f32_e32 v143, v143
	v_pk_add_f32 v[136:137], v[136:137], 1.0 op_sel_hi:[1,0]
	v_pk_add_f32 v[142:143], v[142:143], 1.0 op_sel_hi:[1,0]
	v_rcp_f32_e32 v136, v136
	v_rcp_f32_e32 v137, v137
	v_rcp_f32_e32 v142, v142
	v_rcp_f32_e32 v143, v143
	s_nop 0
	v_pk_mul_f32 v[130:131], v[130:131], v[136:137]
	v_pk_mul_f32 v[138:139], v[138:139], v[142:143]
	v_pk_mul_f32 v[130:131], v[134:135], v[130:131]
	v_pk_mul_f32 v[138:139], v[140:141], v[138:139]
	v_cvt_pk_bf16_f32 v144, v130, v131
	v_cvt_pk_bf16_f32 v145, v138, v139
	v_pk_mul_f32 v[130:131], v[52:53], v[162:163] op_sel:[0,1]
	v_pk_mul_f32 v[138:139], v[54:55], v[162:163] op_sel:[0,1]
	v_pk_mul_f32 v[134:135], v[60:61], v[162:163] op_sel:[0,1]
	v_pk_mul_f32 v[140:141], v[62:63], v[162:163] op_sel:[0,1]
	v_pk_mul_f32 v[136:137], v[130:131], s[10:11]
	v_pk_mul_f32 v[142:143], v[138:139], s[10:11]
	v_exp_f32_e32 v136, v136
	v_exp_f32_e32 v137, v137
	v_exp_f32_e32 v142, v142
	v_exp_f32_e32 v143, v143
	v_pk_add_f32 v[136:137], v[136:137], 1.0 op_sel_hi:[1,0]
	v_pk_add_f32 v[142:143], v[142:143], 1.0 op_sel_hi:[1,0]
	v_rcp_f32_e32 v136, v136
	v_rcp_f32_e32 v137, v137
	v_rcp_f32_e32 v142, v142
	v_rcp_f32_e32 v143, v143
	s_nop 0
	v_pk_mul_f32 v[130:131], v[130:131], v[136:137]
	v_pk_mul_f32 v[138:139], v[138:139], v[142:143]
	v_pk_mul_f32 v[130:131], v[134:135], v[130:131]
	v_pk_mul_f32 v[138:139], v[140:141], v[138:139]
	v_cvt_pk_bf16_f32 v146, v130, v131
	v_cvt_pk_bf16_f32 v147, v138, v139
	s_nop 1
	v_permlane16_swap_b32_e32 v144, v146
	v_permlane16_swap_b32_e32 v145, v147
	global_store_dwordx4 v[132:133], v[144:147], off
	v_lshl_add_u64 v[132:133], v[132:133], 0, s[8:9]
	v_pk_mul_f32 v[130:131], v[32:33], v[162:163] op_sel_hi:[1,0]
	v_pk_mul_f32 v[138:139], v[34:35], v[162:163] op_sel_hi:[1,0]
; __device__ __forceinline__ float sigmoidf_(float x) { return __builtin_amdgcn_rcpf(1.0f + __expf(-x)); }
; __device__ __forceinline__ void gemm_phase(const GemmArgs& a, char* smem) {
;     ...
;     } else if (emode == 1) {
; #pragma unroll
;       for (int ai = 0; ai < 2; ++ai)
; #pragma unroll
;         for (int m = 0; m < 4; ++m) {
;           const int row = brow + ai * 128 + wr * 64 + m * 16 + fr;
;           const float r = rr[ai][m];
; #pragma unroll
;           for (int n = 0; n < 2; ++n) {
;             const int col = (bcol >> 1) + wc * 32 + n * 16 + fq * 4;
;             float h[4];
; #pragma unroll
;             for (int j = 0; j < 4; ++j) {
;               const float g = acc[ai][0][m][n][j] * r, uu = acc[ai][1][m][n][j] * r;
;               h[j] = g * sigmoidf_(g) * uu;
;             }
;             uint2 pk;
;             pk.x = pack2(h[0], h[1]);
;             pk.y = pack2(h[2], h[3]);
;             *(uint2*)(a.outb + (long)row * a.ldo + col) = pk;
;           }
;         }
	v_pk_mul_f32 v[134:135], v[40:41], v[162:163] op_sel_hi:[1,0]
	v_pk_mul_f32 v[140:141], v[42:43], v[162:163] op_sel_hi:[1,0]
	v_pk_mul_f32 v[136:137], v[130:131], s[10:11]
	v_pk_mul_f32 v[142:143], v[138:139], s[10:11]
	v_exp_f32_e32 v136, v136
	v_exp_f32_e32 v137, v137
	v_exp_f32_e32 v142, v142
	v_exp_f32_e32 v143, v143
	v_pk_add_f32 v[136:137], v[136:137], 1.0 op_sel_hi:[1,0]
	v_pk_add_f32 v[142:143], v[142:143], 1.0 op_sel_hi:[1,0]
	v_rcp_f32_e32 v136, v136
	v_rcp_f32_e32 v137, v137
	v_rcp_f32_e32 v142, v142
	v_rcp_f32_e32 v143, v143
	s_nop 0
	v_pk_mul_f32 v[130:131], v[130:131], v[136:137]
	v_pk_mul_f32 v[138:139], v[138:139], v[142:143]
	v_pk_mul_f32 v[130:131], v[134:135], v[130:131]
	v_pk_mul_f32 v[138:139], v[140:141], v[138:139]
	v_cvt_pk_bf16_f32 v148, v130, v131
	v_cvt_pk_bf16_f32 v149, v138, v139
	v_pk_mul_f32 v[130:131], v[36:37], v[162:163] op_sel_hi:[1,0]
	v_pk_mul_f32 v[138:139], v[38:39], v[162:163] op_sel_hi:[1,0]
	v_pk_mul_f32 v[134:135], v[44:45], v[162:163] op_sel_hi:[1,0]
	v_pk_mul_f32 v[140:141], v[46:47], v[162:163] op_sel_hi:[1,0]
	v_pk_mul_f32 v[136:137], v[130:131], s[10:11]
	v_pk_mul_f32 v[142:143], v[138:139], s[10:11]
	v_exp_f32_e32 v136, v136
	v_exp_f32_e32 v137, v137
	v_exp_f32_e32 v142, v142
	v_exp_f32_e32 v143, v143
	v_pk_add_f32 v[136:137], v[136:137], 1.0 op_sel_hi:[1,0]
	v_pk_add_f32 v[142:143], v[142:143], 1.0 op_sel_hi:[1,0]
	v_rcp_f32_e32 v136, v136
	v_rcp_f32_e32 v137, v137
	v_rcp_f32_e32 v142, v142
	v_rcp_f32_e32 v143, v143
	s_nop 0
	v_pk_mul_f32 v[130:131], v[130:131], v[136:137]
	v_pk_mul_f32 v[138:139], v[138:139], v[142:143]
	v_pk_mul_f32 v[130:131], v[134:135], v[130:131]
	v_pk_mul_f32 v[138:139], v[140:141], v[138:139]
	v_cvt_pk_bf16_f32 v150, v130, v131
	v_cvt_pk_bf16_f32 v151, v138, v139
	s_nop 1
	v_permlane16_swap_b32_e32 v148, v150
	v_permlane16_swap_b32_e32 v149, v151
	global_store_dwordx4 v[132:133], v[148:151], off
	v_lshl_add_u64 v[132:133], v[132:133], 0, s[8:9]
	v_pk_mul_f32 v[130:131], v[16:17], v[164:165] op_sel:[0,1]
	v_pk_mul_f32 v[138:139], v[18:19], v[164:165] op_sel:[0,1]
	v_pk_mul_f32 v[134:135], v[24:25], v[164:165] op_sel:[0,1]
	v_pk_mul_f32 v[140:141], v[26:27], v[164:165] op_sel:[0,1]
	v_pk_mul_f32 v[136:137], v[130:131], s[10:11]
	v_pk_mul_f32 v[142:143], v[138:139], s[10:11]
	v_exp_f32_e32 v136, v136
	v_exp_f32_e32 v137, v137
	v_exp_f32_e32 v142, v142
	v_exp_f32_e32 v143, v143
	v_pk_add_f32 v[136:137], v[136:137], 1.0 op_sel_hi:[1,0]
	v_pk_add_f32 v[142:143], v[142:143], 1.0 op_sel_hi:[1,0]
	v_rcp_f32_e32 v136, v136
	v_rcp_f32_e32 v137, v137
	v_rcp_f32_e32 v142, v142
	v_rcp_f32_e32 v143, v143
	s_nop 0
	v_pk_mul_f32 v[130:131], v[130:131], v[136:137]
	v_pk_mul_f32 v[138:139], v[138:139], v[142:143]
	v_pk_mul_f32 v[130:131], v[134:135], v[130:131]
	v_pk_mul_f32 v[138:139], v[140:141], v[138:139]
	v_cvt_pk_bf16_f32 v144, v130, v131
	v_cvt_pk_bf16_f32 v145, v138, v139
	v_pk_mul_f32 v[130:131], v[20:21], v[164:165] op_sel:[0,1]
	v_pk_mul_f32 v[138:139], v[22:23], v[164:165] op_sel:[0,1]
	v_pk_mul_f32 v[134:135], v[28:29], v[164:165] op_sel:[0,1]
	v_pk_mul_f32 v[140:141], v[30:31], v[164:165] op_sel:[0,1]
	v_pk_mul_f32 v[136:137], v[130:131], s[10:11]
	v_pk_mul_f32 v[142:143], v[138:139], s[10:11]
	v_exp_f32_e32 v136, v136
	v_exp_f32_e32 v137, v137
	v_exp_f32_e32 v142, v142
	v_exp_f32_e32 v143, v143
	v_pk_add_f32 v[136:137], v[136:137], 1.0 op_sel_hi:[1,0]
	v_pk_add_f32 v[142:143], v[142:143], 1.0 op_sel_hi:[1,0]
	v_rcp_f32_e32 v136, v136
	v_rcp_f32_e32 v137, v137
	v_rcp_f32_e32 v142, v142
	v_rcp_f32_e32 v143, v143
	s_nop 0
	v_pk_mul_f32 v[130:131], v[130:131], v[136:137]
	v_pk_mul_f32 v[138:139], v[138:139], v[142:143]
	v_pk_mul_f32 v[130:131], v[134:135], v[130:131]
	v_pk_mul_f32 v[138:139], v[140:141], v[138:139]
	v_cvt_pk_bf16_f32 v146, v130, v131
	v_cvt_pk_bf16_f32 v147, v138, v139
	s_nop 1
	v_permlane16_swap_b32_e32 v144, v146
	v_permlane16_swap_b32_e32 v145, v147
	global_store_dwordx4 v[132:133], v[144:147], off
	v_lshl_add_u64 v[132:133], v[132:133], 0, s[8:9]
	v_pk_mul_f32 v[130:131], v[0:1], v[164:165] op_sel_hi:[1,0]
	v_pk_mul_f32 v[138:139], v[2:3], v[164:165] op_sel_hi:[1,0]
	v_pk_mul_f32 v[134:135], v[8:9], v[164:165] op_sel_hi:[1,0]
	v_pk_mul_f32 v[140:141], v[10:11], v[164:165] op_sel_hi:[1,0]
	v_pk_mul_f32 v[136:137], v[130:131], s[10:11]
	v_pk_mul_f32 v[142:143], v[138:139], s[10:11]
	v_exp_f32_e32 v136, v136
	v_exp_f32_e32 v137, v137
	v_exp_f32_e32 v142, v142
	v_exp_f32_e32 v143, v143
	v_pk_add_f32 v[136:137], v[136:137], 1.0 op_sel_hi:[1,0]
	v_pk_add_f32 v[142:143], v[142:143], 1.0 op_sel_hi:[1,0]
	v_rcp_f32_e32 v136, v136
	v_rcp_f32_e32 v137, v137
	v_rcp_f32_e32 v142, v142
	v_rcp_f32_e32 v143, v143
	s_nop 0
	v_pk_mul_f32 v[130:131], v[130:131], v[136:137]
	v_pk_mul_f32 v[138:139], v[138:139], v[142:143]
	v_pk_mul_f32 v[130:131], v[134:135], v[130:131]
	v_pk_mul_f32 v[138:139], v[140:141], v[138:139]
	v_cvt_pk_bf16_f32 v148, v130, v131
	v_cvt_pk_bf16_f32 v149, v138, v139
	v_pk_mul_f32 v[130:131], v[4:5], v[164:165] op_sel_hi:[1,0]
	v_pk_mul_f32 v[138:139], v[6:7], v[164:165] op_sel_hi:[1,0]
	v_pk_mul_f32 v[134:135], v[12:13], v[164:165] op_sel_hi:[1,0]
	v_pk_mul_f32 v[140:141], v[14:15], v[164:165] op_sel_hi:[1,0]
	v_pk_mul_f32 v[136:137], v[130:131], s[10:11]
	v_pk_mul_f32 v[142:143], v[138:139], s[10:11]
	v_exp_f32_e32 v136, v136
	v_exp_f32_e32 v137, v137
	v_exp_f32_e32 v142, v142
	v_exp_f32_e32 v143, v143
	v_pk_add_f32 v[136:137], v[136:137], 1.0 op_sel_hi:[1,0]
	v_pk_add_f32 v[142:143], v[142:143], 1.0 op_sel_hi:[1,0]
	v_rcp_f32_e32 v136, v136
	v_rcp_f32_e32 v137, v137
	v_rcp_f32_e32 v142, v142
	v_rcp_f32_e32 v143, v143
	s_nop 0
	v_pk_mul_f32 v[130:131], v[130:131], v[136:137]
	v_pk_mul_f32 v[138:139], v[138:139], v[142:143]
	v_pk_mul_f32 v[130:131], v[134:135], v[130:131]
	v_pk_mul_f32 v[138:139], v[140:141], v[138:139]
	v_cvt_pk_bf16_f32 v150, v130, v131
	v_cvt_pk_bf16_f32 v151, v138, v139
	s_nop 1
	v_permlane16_swap_b32_e32 v148, v150
	v_permlane16_swap_b32_e32 v149, v151
	global_store_dwordx4 v[132:133], v[148:151], off
